# same as previous plus a guard that applies the scan-item remap only when the grid has 256 workgroups (remap otherwise skipped)
# speedup vs baseline: 1.0094x; 1.0021x over previous
; __global__ void __launch_bounds__(512, 2) hybrid_fwd(Args a) {
;     ...
;             int tid2 = threadIdx.x; asm volatile("" : "+v"(tid2)); const int lane2 = tid2 & 63;
;             const int w = wave * gg + bb; const int NGW2 = gg * 8;
;             for (int rep = 0; rep < REP_SCAN; ++rep) {
;     ...
;             for (int it = w; it < NB * 32 + NDB * 32; it += NGW2) scan_item(wsp, outp, ll, it, lds + wave * SCAN_LDS_WAVE, lane2);
.LBB0_440:
	s_or_b64 exec, exec, s[0:1]
	s_xor_b64 s[0:1], s[52:53], -1
	v_writelane_b32 v255, s0, 41
	s_mov_b32 s14, s88
	s_mov_b64 s[86:87], s[74:75]
	v_writelane_b32 v255, s1, 42
	s_mov_b32 s15, s83
	s_mov_b32 s88, s13
	v_readlane_b32 s0, v255, 5
	s_waitcnt lgkmcnt(0)
	s_barrier
	s_mul_i32 s0, s14, s0
	s_add_i32 s18, s0, s15
	s_lshl_b32 s83, s14, 3
	s_add_u32 s90, s86, 0x33c00000
	v_mov_b32_e32 v0, v242
	s_addc_u32 s91, s87, 0
	s_ashr_i32 s89, s88, 31
	s_cmpk_gt_i32 s18, 0x5ff
	v_and_b32_e32 v234, 63, v0
	s_cbranch_scc1 .LBB0_513
	s_add_u32 s17, s86, 0x1b600000
	s_addc_u32 s16, s87, 0
	s_lshl_b32 s68, s88, 5
	s_add_u32 s92, s90, 0x8100
	s_addc_u32 s93, s91, 0
	s_add_u32 s94, s90, 0x48100
	s_addc_u32 s95, s91, 0
	s_add_u32 s96, s90, 0x88100
	s_addc_u32 s97, s91, 0
	s_add_u32 s52, s90, 0xc8100
	s_addc_u32 s53, s91, 0
	s_lshl_b32 s0, s88, 9
	s_ashr_i32 s1, s0, 31
	s_lshl_b64 s[0:1], s[0:1], 2
	s_add_u32 s0, s90, s0
	s_addc_u32 s1, s91, s1
	s_add_u32 s69, s0, 0x108100
	s_addc_u32 s79, s1, 0
	s_lshl_b64 s[84:85], s[88:89], 9
	s_add_u32 s19, s86, 0x1f70c000
	s_addc_u32 s20, s87, 0
	s_add_u32 s21, s86, 0x1f77c000
	s_addc_u32 s22, s87, 0
	s_mov_b32 s64, s18
	s_mov_b32 s65, s18
	s_cmpk_lg_i32 s83, 0x800
	s_cbranch_scc1 .Lscan_noremap
	s_cmpk_gt_i32 s18, 0x3ff
	s_cbranch_scc1 .Lscan_noremap
	s_and_b32 s64, s18, 7
	s_lshl_b32 s64, s64, 7
	s_lshr_b32 s65, s18, 8
	s_lshl_b32 s65, s65, 5
	s_or_b32 s64, s64, s65
	s_bfe_u32 s65, s18, 0x50003
	s_or_b32 s64, s64, s65
	s_mov_b32 s65, s64
